# P0: eight predicated rrow dword stores merged into one 32-byte store; two compiler vmcnt waits that serialised the weight-item loads ahead of the row loads removed; on top of snake-order attention
# speedup vs baseline: 1.0009x; 1.0009x over previous
; #define GAS __attribute__((address_space(1)))
; __device__ __forceinline__ void p0_prologue(Frame& F) {
;     ...
;         f32x4 v[8][4];
;         if (rows_left) {
; #pragma unroll
;             for (int r = 0; r < 8; ++r) { const GAS f32x4* xr = (const GAS f32x4*)(F.x + (size_t)(m0 + r) * D) + lane;
; #pragma unroll
;                 for (int j = 0; j < 4; ++j) v[r][j] = __builtin_nontemporal_load(xr + 64 * j); }
;         }
.LBB0_53:
	s_ashr_i32 s71, s70, 31
	s_lshl_b64 s[76:77], s[70:71], 12
	s_nop 0
	v_lshl_add_u64 v[84:85], v[166:167], 0, s[76:77]
	s_mov_b64 s[76:77], 0x1000
	v_add_co_u32_e32 v2, vcc, 0x1000, v84
	v_lshl_add_u64 v[0:1], v[84:85], 0, s[76:77]
	s_nop 0
	v_addc_co_u32_e32 v3, vcc, 0, v85, vcc
	global_load_dwordx4 v[16:19], v[84:85], off nt
	global_load_dwordx4 v[12:15], v[84:85], off offset:1024 nt
	global_load_dwordx4 v[8:11], v[84:85], off offset:2048 nt
	global_load_dwordx4 v[4:7], v[84:85], off offset:3072 nt
	global_load_dwordx4 v[36:39], v[0:1], off offset:1024 nt
	global_load_dwordx4 v[32:35], v[0:1], off offset:2048 nt
	global_load_dwordx4 v[48:51], v[2:3], off nt
	global_load_dwordx4 v[44:47], v[0:1], off offset:3072 nt
	s_mov_b64 s[76:77], 0x2000
	v_add_co_u32_e32 v2, vcc, 0x2000, v84
	v_lshl_add_u64 v[0:1], v[84:85], 0, s[76:77]
	s_nop 0
	v_addc_co_u32_e32 v3, vcc, 0, v85, vcc
	global_load_dwordx4 v[68:71], v[0:1], off offset:1024 nt
	global_load_dwordx4 v[64:67], v[0:1], off offset:2048 nt
	global_load_dwordx4 v[80:83], v[2:3], off nt
	global_load_dwordx4 v[76:79], v[0:1], off offset:3072 nt
	s_mov_b64 s[76:77], 0x3000
	v_add_co_u32_e32 v2, vcc, 0x3000, v84
	v_lshl_add_u64 v[0:1], v[84:85], 0, s[76:77]
	s_nop 0
	v_addc_co_u32_e32 v3, vcc, 0, v85, vcc
	global_load_dwordx4 v[104:107], v[0:1], off offset:1024 nt
	global_load_dwordx4 v[100:103], v[0:1], off offset:2048 nt
	global_load_dwordx4 v[112:115], v[2:3], off nt
	global_load_dwordx4 v[108:111], v[0:1], off offset:3072 nt
	v_add_co_u32_e32 v2, vcc, 0x4000, v84
	s_mov_b64 s[76:77], 0x4000
	s_nop 0
	v_addc_co_u32_e32 v3, vcc, 0, v85, vcc
	v_add_co_u32_e32 v30, vcc, 0x5000, v84
	v_lshl_add_u64 v[0:1], v[84:85], 0, s[76:77]
	s_nop 0
	v_addc_co_u32_e32 v31, vcc, 0, v85, vcc
	v_add_co_u32_e32 v62, vcc, 0x6000, v84
	s_mov_b64 s[76:77], 0x5000
	s_nop 0
	v_addc_co_u32_e32 v63, vcc, 0, v85, vcc
	v_lshl_add_u64 v[28:29], v[84:85], 0, s[76:77]
	s_mov_b64 s[76:77], 0x6000
	s_nop 0
	v_add_co_u32_e32 v94, vcc, 0x7000, v84
	v_lshl_add_u64 v[60:61], v[84:85], 0, s[76:77]
	v_lshl_add_u64 v[92:93], v[84:85], 0, s[50:51]
	v_addc_co_u32_e32 v95, vcc, 0, v85, vcc
	global_load_dwordx4 v[120:123], v[0:1], off offset:1024 nt
	global_load_dwordx4 v[116:119], v[0:1], off offset:2048 nt
	global_load_dwordx4 v[124:127], v[2:3], off nt
	s_nop 0
	global_load_dwordx4 v[0:3], v[0:1], off offset:3072 nt
	s_nop 0
	global_load_dwordx4 v[24:27], v[28:29], off offset:1024 nt
	global_load_dwordx4 v[20:23], v[28:29], off offset:2048 nt
	global_load_dwordx4 v[40:43], v[30:31], off nt
	s_nop 0
	global_load_dwordx4 v[28:31], v[28:29], off offset:3072 nt
	s_nop 0
	global_load_dwordx4 v[56:59], v[60:61], off offset:1024 nt
	global_load_dwordx4 v[52:55], v[60:61], off offset:2048 nt
	global_load_dwordx4 v[72:75], v[62:63], off nt
	s_nop 0
	global_load_dwordx4 v[60:63], v[60:61], off offset:3072 nt
	s_nop 0
	global_load_dwordx4 v[88:91], v[92:93], off offset:1024 nt
	global_load_dwordx4 v[84:87], v[92:93], off offset:2048 nt
	global_load_dwordx4 v[96:99], v[94:95], off nt
	s_nop 0
	global_load_dwordx4 v[92:95], v[92:93], off offset:3072 nt

; __device__ __forceinline__ void p0_prologue(Frame& F) {
;     ...
;         if (rows_left) {
;             float s[8];
; #pragma unroll
;             for (int r = 0; r < 8; ++r) { float a = 0.f;
; #pragma unroll
;                 for (int j = 0; j < 4; ++j) a += (v[r][j].x * v[r][j].x + v[r][j].y * v[r][j].y) + (v[r][j].z * v[r][j].z + v[r][j].w * v[r][j].w);
;                 s[r] = a; }
.LBB0_60:
	s_and_b64 vcc, exec, s[10:11]
	s_cbranch_vccnz .LBB0_29
	s_waitcnt vmcnt(31)
	v_mul_f32_e32 v128, v17, v17
	v_mul_f32_e32 v129, v19, v19
	v_fmac_f32_e32 v128, v16, v16
	v_fmac_f32_e32 v129, v18, v18
	v_add_f32_e32 v128, v128, v129
	s_waitcnt vmcnt(30)
	v_mul_f32_e32 v129, v13, v13
	v_mul_f32_e32 v130, v15, v15
	v_fmac_f32_e32 v129, v12, v12
	v_fmac_f32_e32 v130, v14, v14
	v_add_f32_e32 v129, v129, v130
	v_add_f32_e32 v128, v129, v128
	s_waitcnt vmcnt(29)
	v_mul_f32_e32 v129, v9, v9
	v_mul_f32_e32 v130, v11, v11
	v_fmac_f32_e32 v129, v8, v8
	v_fmac_f32_e32 v130, v10, v10
	v_add_f32_e32 v129, v129, v130
	v_add_f32_e32 v128, v129, v128
	s_waitcnt vmcnt(28)
	v_mul_f32_e32 v129, v5, v5
	v_mul_f32_e32 v130, v7, v7
	v_fmac_f32_e32 v129, v4, v4
	v_fmac_f32_e32 v130, v6, v6
	v_add_f32_e32 v129, v129, v130
	v_add_f32_e32 v128, v129, v128
	s_waitcnt vmcnt(25)
	v_mul_f32_e32 v129, v49, v49
	v_mul_f32_e32 v130, v51, v51
	v_fmac_f32_e32 v129, v48, v48
	v_fmac_f32_e32 v130, v50, v50
	v_add_f32_e32 v129, v129, v130
	v_mul_f32_e32 v130, v37, v37
	v_mul_f32_e32 v131, v39, v39
	v_fmac_f32_e32 v130, v36, v36
	v_fmac_f32_e32 v131, v38, v38
	v_add_f32_e32 v130, v130, v131
	v_add_f32_e32 v129, v130, v129
	v_mul_f32_e32 v130, v33, v33
	v_mul_f32_e32 v131, v35, v35
	v_fmac_f32_e32 v130, v32, v32
	v_fmac_f32_e32 v131, v34, v34
	v_add_f32_e32 v130, v130, v131
	v_add_f32_e32 v129, v130, v129
	s_waitcnt vmcnt(24)
	v_mul_f32_e32 v130, v45, v45
	v_mul_f32_e32 v131, v47, v47
	v_fmac_f32_e32 v130, v44, v44
	v_fmac_f32_e32 v131, v46, v46
	v_add_f32_e32 v130, v130, v131
	v_add_f32_e32 v129, v130, v129
	s_waitcnt vmcnt(21)
	v_mul_f32_e32 v130, v81, v81
	v_mul_f32_e32 v131, v83, v83
	v_fmac_f32_e32 v130, v80, v80
	v_fmac_f32_e32 v131, v82, v82
	v_add_f32_e32 v130, v130, v131
	v_mul_f32_e32 v131, v69, v69
	v_mul_f32_e32 v132, v71, v71
	v_fmac_f32_e32 v131, v68, v68
	v_fmac_f32_e32 v132, v70, v70
	v_add_f32_e32 v131, v131, v132
	v_add_f32_e32 v130, v131, v130
	v_mul_f32_e32 v131, v65, v65
	v_mul_f32_e32 v132, v67, v67
	v_fmac_f32_e32 v131, v64, v64
	v_fmac_f32_e32 v132, v66, v66
	v_add_f32_e32 v131, v131, v132
	v_add_f32_e32 v130, v131, v130
	s_waitcnt vmcnt(20)
	v_mul_f32_e32 v131, v77, v77
	v_mul_f32_e32 v132, v79, v79
	v_fmac_f32_e32 v131, v76, v76
	v_fmac_f32_e32 v132, v78, v78
	v_add_f32_e32 v131, v131, v132
	v_add_f32_e32 v130, v131, v130
	s_waitcnt vmcnt(17)
	v_mul_f32_e32 v131, v113, v113
	v_mul_f32_e32 v132, v115, v115
	v_fmac_f32_e32 v131, v112, v112
	v_fmac_f32_e32 v132, v114, v114
	v_add_f32_e32 v131, v131, v132
	v_mul_f32_e32 v132, v105, v105
	v_mul_f32_e32 v133, v107, v107
	v_fmac_f32_e32 v132, v104, v104
	v_fmac_f32_e32 v133, v106, v106
	v_add_f32_e32 v132, v132, v133
	v_add_f32_e32 v131, v132, v131
	v_mul_f32_e32 v132, v101, v101
	v_mul_f32_e32 v133, v103, v103
	v_fmac_f32_e32 v132, v100, v100
	v_fmac_f32_e32 v133, v102, v102
	v_add_f32_e32 v132, v132, v133
	v_add_f32_e32 v131, v132, v131
	s_waitcnt vmcnt(16)
	v_mul_f32_e32 v132, v109, v109
	v_mul_f32_e32 v133, v111, v111
	v_fmac_f32_e32 v132, v108, v108
	v_fmac_f32_e32 v133, v110, v110
	v_add_f32_e32 v132, v132, v133
	v_add_f32_e32 v131, v132, v131
	s_waitcnt vmcnt(13)
	v_mul_f32_e32 v132, v125, v125
	v_mul_f32_e32 v133, v127, v127
	v_fmac_f32_e32 v132, v124, v124
	v_fmac_f32_e32 v133, v126, v126
	v_add_f32_e32 v132, v132, v133
	v_mul_f32_e32 v133, v121, v121
	v_mul_f32_e32 v134, v123, v123
	v_fmac_f32_e32 v133, v120, v120
	v_fmac_f32_e32 v134, v122, v122
	v_add_f32_e32 v133, v133, v134
	v_add_f32_e32 v132, v133, v132
	v_mul_f32_e32 v133, v117, v117
	v_mul_f32_e32 v134, v119, v119
	v_fmac_f32_e32 v133, v116, v116
	v_fmac_f32_e32 v134, v118, v118
	v_add_f32_e32 v133, v133, v134
	v_add_f32_e32 v132, v133, v132
	s_waitcnt vmcnt(12)
	v_mul_f32_e32 v133, v1, v1
	v_mul_f32_e32 v134, v3, v3
	v_fmac_f32_e32 v133, v0, v0
	v_fmac_f32_e32 v134, v2, v2
	v_add_f32_e32 v133, v133, v134
	v_add_f32_e32 v132, v133, v132
	s_waitcnt vmcnt(9)
	v_mul_f32_e32 v133, v41, v41
	v_mul_f32_e32 v134, v43, v43
	v_fmac_f32_e32 v133, v40, v40
	v_fmac_f32_e32 v134, v42, v42
	v_add_f32_e32 v133, v133, v134
	v_mul_f32_e32 v134, v25, v25
	v_mul_f32_e32 v135, v27, v27
	v_fmac_f32_e32 v134, v24, v24
	v_fmac_f32_e32 v135, v26, v26
	v_add_f32_e32 v134, v134, v135
	v_add_f32_e32 v133, v134, v133
	v_mul_f32_e32 v134, v21, v21
	v_mul_f32_e32 v135, v23, v23
	v_fmac_f32_e32 v134, v20, v20
	v_fmac_f32_e32 v135, v22, v22
	v_add_f32_e32 v134, v134, v135
	v_add_f32_e32 v133, v134, v133
	s_waitcnt vmcnt(8)
	v_mul_f32_e32 v134, v29, v29
	v_mul_f32_e32 v135, v31, v31
	v_fmac_f32_e32 v134, v28, v28
	v_fmac_f32_e32 v135, v30, v30
	v_add_f32_e32 v134, v134, v135
	v_add_f32_e32 v133, v134, v133
	s_waitcnt vmcnt(5)
	v_mul_f32_e32 v134, v73, v73
	v_mul_f32_e32 v135, v75, v75
	v_fmac_f32_e32 v134, v72, v72
	v_fmac_f32_e32 v135, v74, v74
	v_add_f32_e32 v134, v134, v135
	v_mul_f32_e32 v135, v57, v57
	v_mul_f32_e32 v136, v59, v59
	v_fmac_f32_e32 v135, v56, v56
	v_fmac_f32_e32 v136, v58, v58
	v_add_f32_e32 v135, v135, v136
	v_add_f32_e32 v134, v135, v134
	v_mul_f32_e32 v135, v53, v53
	v_mul_f32_e32 v136, v55, v55
	v_fmac_f32_e32 v135, v52, v52
	v_fmac_f32_e32 v136, v54, v54
	v_add_f32_e32 v135, v135, v136
	v_add_f32_e32 v134, v135, v134
	s_waitcnt vmcnt(4)
	v_mul_f32_e32 v135, v61, v61
	v_mul_f32_e32 v136, v63, v63
	v_fmac_f32_e32 v135, v60, v60
	v_fmac_f32_e32 v136, v62, v62
	v_add_f32_e32 v135, v135, v136
	v_add_f32_e32 v134, v135, v134
	s_waitcnt vmcnt(1)
; __device__ __forceinline__ void p0_prologue(Frame& F) {
;     ...
;             for (int r = 0; r < 8; ++r) { float a = 0.f;
; #pragma unroll
;                 for (int j = 0; j < 4; ++j) a += (v[r][j].x * v[r][j].x + v[r][j].y * v[r][j].y) + (v[r][j].z * v[r][j].z + v[r][j].w * v[r][j].w);
;                 s[r] = a; }
; #pragma unroll
;             for (int o = 1; o < 64; o <<= 1) {
; #pragma unroll
;                 for (int r = 0; r < 8; ++r) s[r] += __shfl_xor(s[r], o); }
	v_mul_f32_e32 v135, v97, v97
	v_mul_f32_e32 v136, v99, v99
	v_fmac_f32_e32 v135, v96, v96
	v_fmac_f32_e32 v136, v98, v98
	v_add_f32_e32 v135, v135, v136
	v_mul_f32_e32 v136, v89, v89
	v_mul_f32_e32 v137, v91, v91
	v_fmac_f32_e32 v136, v88, v88
	v_fmac_f32_e32 v137, v90, v90
	v_add_f32_e32 v136, v136, v137
	v_add_f32_e32 v135, v136, v135
	v_mul_f32_e32 v136, v85, v85
	v_mul_f32_e32 v137, v87, v87
	v_fmac_f32_e32 v136, v84, v84
	v_fmac_f32_e32 v137, v86, v86
	v_add_f32_e32 v136, v136, v137
	v_and_b32_e32 v137, 64, v223
	v_add_u32_e32 v138, 64, v137
	v_xor_b32_e32 v137, 1, v223
	v_cmp_lt_i32_e32 vcc, v137, v138
	v_add_f32_e32 v135, v136, v135
	s_waitcnt vmcnt(0)
	v_mul_f32_e32 v136, v93, v93
	v_cndmask_b32_e32 v137, v223, v137, vcc
	v_lshlrev_b32_e32 v137, 2, v137
	ds_bpermute_b32 v139, v137, v128
	v_mul_f32_e32 v140, v95, v95
	v_fmac_f32_e32 v136, v92, v92
	v_fmac_f32_e32 v140, v94, v94
	v_add_f32_e32 v136, v136, v140
	v_add_f32_e32 v135, v136, v135
	s_waitcnt lgkmcnt(0)
	v_add_f32_e32 v128, v128, v139
	ds_bpermute_b32 v136, v137, v129
	ds_bpermute_b32 v139, v137, v130
	ds_bpermute_b32 v140, v137, v131
	ds_bpermute_b32 v141, v137, v132
	ds_bpermute_b32 v142, v137, v133
	s_waitcnt lgkmcnt(4)
	v_add_f32_e32 v129, v129, v136
	s_waitcnt lgkmcnt(3)
	v_add_f32_e32 v130, v130, v139
	ds_bpermute_b32 v136, v137, v134
	v_xor_b32_e32 v139, 2, v223
	v_cmp_lt_i32_e32 vcc, v139, v138
	s_waitcnt lgkmcnt(3)
	v_add_f32_e32 v131, v131, v140
	ds_bpermute_b32 v137, v137, v135
	v_cndmask_b32_e32 v139, v223, v139, vcc
	v_lshlrev_b32_e32 v139, 2, v139
	ds_bpermute_b32 v140, v139, v128
	s_waitcnt lgkmcnt(2)
	v_add_f32_e32 v134, v134, v136
	ds_bpermute_b32 v136, v139, v131
	v_add_f32_e32 v132, v132, v141
	ds_bpermute_b32 v141, v139, v129
	v_add_f32_e32 v133, v133, v142
	ds_bpermute_b32 v142, v139, v130
	s_waitcnt lgkmcnt(3)
	v_add_f32_e32 v128, v128, v140
	ds_bpermute_b32 v140, v139, v133
	s_waitcnt lgkmcnt(3)
	v_add_f32_e32 v131, v131, v136
	v_xor_b32_e32 v136, 4, v223
	v_add_f32_e32 v135, v135, v137
	v_cmp_lt_i32_e32 vcc, v136, v138
	s_waitcnt lgkmcnt(2)
	v_add_f32_e32 v129, v129, v141
	ds_bpermute_b32 v137, v139, v132
	ds_bpermute_b32 v141, v139, v134
	ds_bpermute_b32 v139, v139, v135
	v_cndmask_b32_e32 v136, v223, v136, vcc
	s_waitcnt lgkmcnt(4)
	v_add_f32_e32 v130, v130, v142
	v_lshlrev_b32_e32 v136, 2, v136
	s_waitcnt lgkmcnt(3)
	v_add_f32_e32 v133, v133, v140
	ds_bpermute_b32 v140, v136, v130
	s_waitcnt lgkmcnt(3)
	v_add_f32_e32 v132, v132, v137
	s_waitcnt lgkmcnt(1)
	v_add_f32_e32 v135, v135, v139
	ds_bpermute_b32 v137, v136, v128
	ds_bpermute_b32 v139, v136, v129
	ds_bpermute_b32 v142, v136, v132
	s_waitcnt lgkmcnt(3)
	v_add_f32_e32 v130, v130, v140
	v_xor_b32_e32 v140, 8, v223
	v_cmp_lt_i32_e32 vcc, v140, v138
	v_add_f32_e32 v134, v134, v141
	ds_bpermute_b32 v141, v136, v131
	v_cndmask_b32_e32 v140, v223, v140, vcc
	s_waitcnt lgkmcnt(3)
	v_add_f32_e32 v128, v128, v137
	s_waitcnt lgkmcnt(2)
	v_add_f32_e32 v129, v129, v139
	ds_bpermute_b32 v137, v136, v133
	ds_bpermute_b32 v139, v136, v134
	v_lshlrev_b32_e32 v140, 2, v140
	s_waitcnt lgkmcnt(3)
	v_add_f32_e32 v132, v132, v142
	ds_bpermute_b32 v136, v136, v135
	ds_bpermute_b32 v142, v140, v129
	s_waitcnt lgkmcnt(4)
	v_add_f32_e32 v131, v131, v141
	ds_bpermute_b32 v141, v140, v128
	s_waitcnt lgkmcnt(4)
	v_add_f32_e32 v133, v133, v137
	s_waitcnt lgkmcnt(3)
	v_add_f32_e32 v134, v134, v139
	ds_bpermute_b32 v137, v140, v131
	s_waitcnt lgkmcnt(3)
	v_add_f32_e32 v135, v135, v136
	s_waitcnt lgkmcnt(2)
; __device__ __forceinline__ void p0_prologue(Frame& F) {
;     ...
; #pragma unroll
;             for (int o = 1; o < 64; o <<= 1) {
; #pragma unroll
;                 for (int r = 0; r < 8; ++r) s[r] += __shfl_xor(s[r], o); }
;             float rs8[8];
; #pragma unroll
;             for (int r = 0; r < 8; ++r) { const float ms = s[r] * (1.f / D) + EPS; rs8[r] = __builtin_amdgcn_rsqf(ms); if (lane == 0) F.rrow[m0 + r] = ms * rs8[r]; }
	v_add_f32_e32 v129, v129, v142
	ds_bpermute_b32 v136, v140, v130
	ds_bpermute_b32 v142, v140, v134
	s_waitcnt lgkmcnt(3)
	v_add_f32_e32 v128, v128, v141
	ds_bpermute_b32 v139, v140, v132
	ds_bpermute_b32 v141, v140, v133
	s_waitcnt lgkmcnt(4)
	v_add_f32_e32 v131, v131, v137
	v_xor_b32_e32 v137, 16, v223
	s_waitcnt lgkmcnt(3)
	v_add_f32_e32 v130, v130, v136
	s_waitcnt lgkmcnt(2)
	v_add_f32_e32 v136, v134, v142
	ds_bpermute_b32 v134, v140, v135
	v_cmp_lt_i32_e32 vcc, v137, v138
	s_waitcnt lgkmcnt(2)
	v_add_f32_e32 v132, v132, v139
	s_waitcnt lgkmcnt(1)
	v_add_f32_e32 v133, v133, v141
	v_cndmask_b32_e32 v137, v223, v137, vcc
	v_lshlrev_b32_e32 v140, 2, v137
	ds_bpermute_b32 v137, v140, v128
	ds_bpermute_b32 v142, v140, v131
	ds_bpermute_b32 v139, v140, v129
	ds_bpermute_b32 v141, v140, v130
	s_waitcnt lgkmcnt(4)
	v_add_f32_e32 v143, v135, v134
	v_xor_b32_e32 v134, 32, v223
	v_cmp_lt_i32_e32 vcc, v134, v138
	s_waitcnt lgkmcnt(3)
	v_add_f32_e32 v152, v128, v137
	s_waitcnt lgkmcnt(2)
	v_add_f32_e32 v135, v131, v142
	v_cndmask_b32_e32 v134, v223, v134, vcc
	v_lshlrev_b32_e32 v142, 2, v134
	s_waitcnt lgkmcnt(1)
	v_add_f32_e32 v139, v129, v139
	s_waitcnt lgkmcnt(0)
	v_add_f32_e32 v137, v130, v141
	ds_bpermute_b32 v128, v140, v132
	ds_bpermute_b32 v129, v140, v133
	ds_bpermute_b32 v130, v140, v136
	ds_bpermute_b32 v131, v140, v143
	ds_bpermute_b32 v138, v142, v152
	s_waitcnt lgkmcnt(4)
	v_add_f32_e32 v134, v132, v128
	s_waitcnt lgkmcnt(3)
	v_add_f32_e32 v132, v133, v129
	s_waitcnt lgkmcnt(2)
	v_add_f32_e32 v130, v136, v130
	s_waitcnt lgkmcnt(1)
	v_add_f32_e32 v128, v143, v131
	s_waitcnt lgkmcnt(0)
	v_add_f32_e32 v143, v152, v138
	ds_bpermute_b32 v141, v142, v139
	ds_bpermute_b32 v140, v142, v137
	ds_bpermute_b32 v138, v142, v135
	ds_bpermute_b32 v136, v142, v134
	ds_bpermute_b32 v133, v142, v132
	ds_bpermute_b32 v131, v142, v130
	ds_bpermute_b32 v129, v142, v128
	v_fmamk_f32 v142, v143, 0x3a800000, v225
	v_rsq_f32_e32 v214, v142
	s_nop 0
	v_mul_f32_e32 v142, v142, v214
	s_waitcnt lgkmcnt(6)
	v_add_f32_e32 v139, v139, v141
	v_fmamk_f32 v139, v139, 0x3a800000, v225
	v_rsq_f32_e32 v216, v139
	s_nop 0
	v_mul_f32_e32 v139, v139, v216
	s_waitcnt lgkmcnt(5)
	v_add_f32_e32 v137, v137, v140
	v_fmamk_f32 v137, v137, 0x3a800000, v225
	v_rsq_f32_e32 v210, v137
	s_nop 0
	v_mul_f32_e32 v137, v137, v210
	s_waitcnt lgkmcnt(4)
	v_add_f32_e32 v135, v135, v138
	v_fmamk_f32 v135, v135, 0x3a800000, v225
	v_rsq_f32_e32 v212, v135
	s_nop 0
	v_mul_f32_e32 v135, v135, v212
	s_waitcnt lgkmcnt(3)
	v_add_f32_e32 v134, v134, v136
	v_fmamk_f32 v134, v134, 0x3a800000, v225
	v_rsq_f32_e32 v204, v134
	s_nop 0
	v_mul_f32_e32 v134, v134, v204
	s_waitcnt lgkmcnt(2)
	v_add_f32_e32 v132, v132, v133
	v_fmamk_f32 v132, v132, 0x3a800000, v225
	v_rsq_f32_e32 v206, v132
	s_nop 0
	v_mul_f32_e32 v132, v132, v206
	s_waitcnt lgkmcnt(1)
	v_add_f32_e32 v130, v130, v131
	v_fmamk_f32 v130, v130, 0x3a800000, v225
	v_rsq_f32_e32 v200, v130
	s_nop 0
	v_mul_f32_e32 v130, v130, v200
	s_waitcnt lgkmcnt(0)
	v_add_f32_e32 v128, v128, v129
	v_fmamk_f32 v128, v128, 0x3a800000, v225
	v_rsq_f32_e32 v202, v128
	s_nop 0
	v_mul_f32_e32 v128, v128, v202
	s_ashr_i32 s71, s70, 31
	s_lshl_b64 s[0:1], s[70:71], 2
	s_add_u32 s0, s60, s0
	s_addc_u32 s1, s61, s1
	v_cmp_eq_u32_e32 vcc, 1, v223
	v_lshlrev_b32_e32 v129, 4, v223
	s_nop 0
	v_cndmask_b32_e32 v140, v142, v134, vcc
	v_cndmask_b32_e32 v141, v139, v132, vcc
	v_cndmask_b32_e32 v142, v137, v130, vcc
	v_cndmask_b32_e32 v143, v135, v128, vcc
	s_mov_b64 s[8:9], exec
	s_mov_b64 exec, 3
	global_store_dwordx4 v129, v[140:143], s[0:1]
	s_branch .LBB0_28
